# v9 + MODE0 GEMM epilogues store straight from accumulators (permlane16_swap widened dwordx4 stores), no LDS staging
# baseline (speedup 1.0000x reference)
; DI void stb8(bf16_t* p, const F8& f) { *(uint4*)p = pack8(f); }
; template <int MODE>
; DI void gemm_epilogue(const float* Cs, int m0, int n0, const Epi& ep) {
;     ...
; #pragma unroll
;         for (int it = 0; it < 4; ++it) {
;             const int row = (tid >> 4) + 32 * it, cc = (tid & 15) * 8;
;             stb8(ep.b0 + (size_t)(m0 + row) * ep.ld + n0 + cc, ldf8(Cs + row * LDC + cc));
;         }
; template <int MODE>
; DI void gemm_phase(const bf16_t* __restrict__ A, const bf16_t* __restrict__ Bt, int M, int N, int K, const Epi& ep) {
;     ...
; #pragma unroll
;         for (int ai = 0; ai < 2; ++ai)
; #pragma unroll
;             for (int bj = 0; bj < 2; ++bj) {
; #pragma unroll
;                 for (int m = 0; m < 4; ++m)
; #pragma unroll
;                     for (int n = 0; n < 2; ++n)
;                         *(f32x4*)(Cs + (wr * 64 + m * 16 + fr) * LDC + wc * 32 + n * 16 + fq * 4) = acc[ai][bj][m][n];
;                 __syncthreads();
;                 gemm_epilogue<MODE>(Cs, brow + ai * 128, bcol + bj * 128, ep);
;                 __syncthreads();
.LBB0_480:
	s_or_b64 exec, exec, s[6:7]
	v_mov_b32_e32 v64, v250
	s_waitcnt vmcnt(0)
	s_barrier
	v_and_b32_e32 v64, 15, v250
	v_lshrrev_b32_e32 v66, 8, v250
	v_bfe_u32 v67, v250, 5, 1
	v_lshl_add_u32 v64, v66, 6, v64
	v_bfe_u32 v66, v250, 4, 1
	v_bfe_u32 v212, v250, 6, 2
	v_add_u32_e32 v64, s26, v64
	v_lshlrev_b32_e32 v66, 4, v66
	v_lshl_or_b32 v66, v67, 3, v66
	v_lshlrev_b32_e32 v64, 10, v64
	v_lshl_or_b32 v66, v212, 5, v66
	v_add3_u32 v64, v64, v66, s0
	v_lshlrev_b32_e32 v65, 1, v64
	v_cvt_pk_bf16_f32 v96, v96, v97
	v_cvt_pk_bf16_f32 v97, v98, v99
	v_cvt_pk_bf16_f32 v98, v100, v101
	v_cvt_pk_bf16_f32 v99, v102, v103
	v_cvt_pk_bf16_f32 v222, v222, v223
	v_cvt_pk_bf16_f32 v223, v224, v225
	v_cvt_pk_bf16_f32 v224, v68, v69
	v_cvt_pk_bf16_f32 v225, v70, v71
	v_permlane16_swap_b32_e32 v96, v98
	v_permlane16_swap_b32_e32 v97, v99
	v_permlane16_swap_b32_e32 v222, v224
	v_permlane16_swap_b32_e32 v223, v225
	global_store_dwordx4 v65, v[96:99], s[76:77] offset:0
	global_store_dwordx4 v65, v[222:225], s[76:77] offset:256
	v_add_u32_e32 v66, 0x8000, v65
	v_cvt_pk_bf16_f32 v104, v104, v105
	v_cvt_pk_bf16_f32 v105, v106, v107
	v_cvt_pk_bf16_f32 v106, v108, v109
	v_cvt_pk_bf16_f32 v107, v110, v111
	v_cvt_pk_bf16_f32 v72, v72, v73
	v_cvt_pk_bf16_f32 v73, v74, v75
	v_cvt_pk_bf16_f32 v74, v76, v77
	v_cvt_pk_bf16_f32 v75, v78, v79
	v_permlane16_swap_b32_e32 v104, v106
	v_permlane16_swap_b32_e32 v105, v107
	v_permlane16_swap_b32_e32 v72, v74
	v_permlane16_swap_b32_e32 v73, v75
	global_store_dwordx4 v66, v[104:107], s[76:77] offset:0
	global_store_dwordx4 v66, v[72:75], s[76:77] offset:256
	v_add_u32_e32 v67, 0x10000, v65
	v_cvt_pk_bf16_f32 v112, v112, v113
	v_cvt_pk_bf16_f32 v113, v114, v115
	v_cvt_pk_bf16_f32 v114, v116, v117
	v_cvt_pk_bf16_f32 v115, v118, v119
	v_cvt_pk_bf16_f32 v80, v80, v81
	v_cvt_pk_bf16_f32 v81, v82, v83
	v_cvt_pk_bf16_f32 v82, v84, v85
	v_cvt_pk_bf16_f32 v83, v86, v87
	v_permlane16_swap_b32_e32 v112, v114
	v_permlane16_swap_b32_e32 v113, v115
	v_permlane16_swap_b32_e32 v80, v82
	v_permlane16_swap_b32_e32 v81, v83
	global_store_dwordx4 v67, v[112:115], s[76:77] offset:0
	global_store_dwordx4 v67, v[80:83], s[76:77] offset:256
	v_add_u32_e32 v66, 0x18000, v65
	v_cvt_pk_bf16_f32 v120, v120, v121
	v_cvt_pk_bf16_f32 v121, v122, v123
	v_cvt_pk_bf16_f32 v122, v124, v125
	v_cvt_pk_bf16_f32 v123, v126, v127
	v_cvt_pk_bf16_f32 v88, v88, v89
	v_cvt_pk_bf16_f32 v89, v90, v91
	v_cvt_pk_bf16_f32 v90, v92, v93
	v_cvt_pk_bf16_f32 v91, v94, v95
	v_permlane16_swap_b32_e32 v120, v122
	v_permlane16_swap_b32_e32 v121, v123
	v_permlane16_swap_b32_e32 v88, v90
	v_permlane16_swap_b32_e32 v89, v91
	global_store_dwordx4 v66, v[120:123], s[76:77] offset:0
	global_store_dwordx4 v66, v[88:91], s[76:77] offset:256
	v_add_u32_e32 v67, 0x40000, v65
	v_cvt_pk_bf16_f32 v32, v32, v33
	v_cvt_pk_bf16_f32 v33, v34, v35
	v_cvt_pk_bf16_f32 v34, v36, v37
	v_cvt_pk_bf16_f32 v35, v38, v39
	v_cvt_pk_bf16_f32 v0, v0, v1
	v_cvt_pk_bf16_f32 v1, v2, v3
	v_cvt_pk_bf16_f32 v2, v4, v5
	v_cvt_pk_bf16_f32 v3, v6, v7
	v_permlane16_swap_b32_e32 v32, v34
	v_permlane16_swap_b32_e32 v33, v35
	v_permlane16_swap_b32_e32 v0, v2
	v_permlane16_swap_b32_e32 v1, v3
	global_store_dwordx4 v67, v[32:35], s[76:77] offset:0
	global_store_dwordx4 v67, v[0:3], s[76:77] offset:256
	v_add_u32_e32 v66, 0x48000, v65
	v_cvt_pk_bf16_f32 v40, v40, v41
	v_cvt_pk_bf16_f32 v41, v42, v43
	v_cvt_pk_bf16_f32 v42, v44, v45
	v_cvt_pk_bf16_f32 v43, v46, v47
	v_cvt_pk_bf16_f32 v8, v8, v9
	v_cvt_pk_bf16_f32 v9, v10, v11
	v_cvt_pk_bf16_f32 v10, v12, v13
	v_cvt_pk_bf16_f32 v11, v14, v15
	v_permlane16_swap_b32_e32 v40, v42
	v_permlane16_swap_b32_e32 v41, v43
	v_permlane16_swap_b32_e32 v8, v10
	v_permlane16_swap_b32_e32 v9, v11
	global_store_dwordx4 v66, v[40:43], s[76:77] offset:0
	global_store_dwordx4 v66, v[8:11], s[76:77] offset:256
	v_add_u32_e32 v67, 0x50000, v65
	v_cvt_pk_bf16_f32 v48, v48, v49
	v_cvt_pk_bf16_f32 v49, v50, v51
	v_cvt_pk_bf16_f32 v50, v52, v53
	v_cvt_pk_bf16_f32 v51, v54, v55
	v_cvt_pk_bf16_f32 v16, v16, v17
	v_cvt_pk_bf16_f32 v17, v18, v19
	v_cvt_pk_bf16_f32 v18, v20, v21
	v_cvt_pk_bf16_f32 v19, v22, v23
	v_permlane16_swap_b32_e32 v48, v50
	v_permlane16_swap_b32_e32 v49, v51
	v_permlane16_swap_b32_e32 v16, v18
	v_permlane16_swap_b32_e32 v17, v19
	global_store_dwordx4 v67, v[48:51], s[76:77] offset:0
	global_store_dwordx4 v67, v[16:19], s[76:77] offset:256
	v_add_u32_e32 v66, 0x58000, v65
	v_cvt_pk_bf16_f32 v56, v56, v57
	v_cvt_pk_bf16_f32 v57, v58, v59
	v_cvt_pk_bf16_f32 v58, v60, v61
	v_cvt_pk_bf16_f32 v59, v62, v63
	v_cvt_pk_bf16_f32 v24, v24, v25
	v_cvt_pk_bf16_f32 v25, v26, v27
	v_cvt_pk_bf16_f32 v26, v28, v29
	v_cvt_pk_bf16_f32 v27, v30, v31
	v_permlane16_swap_b32_e32 v56, v58
	v_permlane16_swap_b32_e32 v57, v59
	v_permlane16_swap_b32_e32 v24, v26
	v_permlane16_swap_b32_e32 v25, v27
	global_store_dwordx4 v66, v[56:59], s[76:77] offset:0
	global_store_dwordx4 v66, v[24:27], s[76:77] offset:256
	s_add_i32 s22, s22, 1
	s_mul_i32 s0, s22, s18
	s_add_i32 s0, s0, s19
	s_cmpk_lt_i32 s0, 0x200
	s_barrier
	s_cbranch_scc0 .LBB0_491

; DI void stb8(bf16_t* p, const F8& f) { *(uint4*)p = pack8(f); }
; template <int MODE>
; DI void gemm_epilogue(const float* Cs, int m0, int n0, const Epi& ep) {
;     ...
; #pragma unroll
;         for (int it = 0; it < 4; ++it) {
;             const int row = (tid >> 4) + 32 * it, cc = (tid & 15) * 8;
;             stb8(ep.b0 + (size_t)(m0 + row) * ep.ld + n0 + cc, ldf8(Cs + row * LDC + cc));
;         }
; template <int MODE>
; DI void gemm_phase(const bf16_t* __restrict__ A, const bf16_t* __restrict__ Bt, int M, int N, int K, const Epi& ep) {
;     ...
; #pragma unroll
;         for (int ai = 0; ai < 2; ++ai)
; #pragma unroll
;             for (int bj = 0; bj < 2; ++bj) {
; #pragma unroll
;                 for (int m = 0; m < 4; ++m)
; #pragma unroll
;                     for (int n = 0; n < 2; ++n)
;                         *(f32x4*)(Cs + (wr * 64 + m * 16 + fr) * LDC + wc * 32 + n * 16 + fq * 4) = acc[ai][bj][m][n];
;                 __syncthreads();
;                 gemm_epilogue<MODE>(Cs, brow + ai * 128, bcol + bj * 128, ep);
;                 __syncthreads();
.LBB0_550:
	s_or_b64 exec, exec, s[6:7]
	v_mov_b32_e32 v64, v250
	s_waitcnt vmcnt(0)
	s_barrier
	v_and_b32_e32 v64, 15, v250
	v_lshrrev_b32_e32 v66, 8, v250
	v_bfe_u32 v67, v250, 5, 1
	v_lshl_add_u32 v64, v66, 6, v64
	v_bfe_u32 v66, v250, 4, 1
	v_bfe_u32 v212, v250, 6, 2
	v_add_u32_e32 v64, s22, v64
	v_lshlrev_b32_e32 v66, 4, v66
	v_lshl_or_b32 v66, v67, 3, v66
	v_mul_u32_u24_e32 v64, 0x900, v64
	v_lshl_or_b32 v66, v212, 5, v66
	v_add3_u32 v64, v64, v66, s0
	v_lshlrev_b32_e32 v65, 1, v64
	v_cvt_pk_bf16_f32 v96, v96, v97
	v_cvt_pk_bf16_f32 v97, v98, v99
	v_cvt_pk_bf16_f32 v98, v100, v101
	v_cvt_pk_bf16_f32 v99, v102, v103
	v_cvt_pk_bf16_f32 v160, v160, v161
	v_cvt_pk_bf16_f32 v161, v162, v163
	v_cvt_pk_bf16_f32 v162, v68, v69
	v_cvt_pk_bf16_f32 v163, v70, v71
	v_permlane16_swap_b32_e32 v96, v98
	v_permlane16_swap_b32_e32 v97, v99
	v_permlane16_swap_b32_e32 v160, v162
	v_permlane16_swap_b32_e32 v161, v163
	global_store_dwordx4 v65, v[96:99], s[84:85] offset:0
	global_store_dwordx4 v65, v[160:163], s[84:85] offset:256
	v_add_u32_e32 v66, 0x12000, v65
	v_cvt_pk_bf16_f32 v104, v104, v105
	v_cvt_pk_bf16_f32 v105, v106, v107
	v_cvt_pk_bf16_f32 v106, v108, v109
	v_cvt_pk_bf16_f32 v107, v110, v111
	v_cvt_pk_bf16_f32 v72, v72, v73
	v_cvt_pk_bf16_f32 v73, v74, v75
	v_cvt_pk_bf16_f32 v74, v76, v77
	v_cvt_pk_bf16_f32 v75, v78, v79
	v_permlane16_swap_b32_e32 v104, v106
	v_permlane16_swap_b32_e32 v105, v107
	v_permlane16_swap_b32_e32 v72, v74
	v_permlane16_swap_b32_e32 v73, v75
	global_store_dwordx4 v66, v[104:107], s[84:85] offset:0
	global_store_dwordx4 v66, v[72:75], s[84:85] offset:256
	v_add_u32_e32 v67, 0x24000, v65
	v_cvt_pk_bf16_f32 v112, v112, v113
	v_cvt_pk_bf16_f32 v113, v114, v115
	v_cvt_pk_bf16_f32 v114, v116, v117
	v_cvt_pk_bf16_f32 v115, v118, v119
	v_cvt_pk_bf16_f32 v80, v80, v81
	v_cvt_pk_bf16_f32 v81, v82, v83
	v_cvt_pk_bf16_f32 v82, v84, v85
	v_cvt_pk_bf16_f32 v83, v86, v87
	v_permlane16_swap_b32_e32 v112, v114
	v_permlane16_swap_b32_e32 v113, v115
	v_permlane16_swap_b32_e32 v80, v82
	v_permlane16_swap_b32_e32 v81, v83
	global_store_dwordx4 v67, v[112:115], s[84:85] offset:0
	global_store_dwordx4 v67, v[80:83], s[84:85] offset:256
	v_add_u32_e32 v66, 0x36000, v65
	v_cvt_pk_bf16_f32 v120, v120, v121
	v_cvt_pk_bf16_f32 v121, v122, v123
	v_cvt_pk_bf16_f32 v122, v124, v125
	v_cvt_pk_bf16_f32 v123, v126, v127
	v_cvt_pk_bf16_f32 v88, v88, v89
	v_cvt_pk_bf16_f32 v89, v90, v91
	v_cvt_pk_bf16_f32 v90, v92, v93
	v_cvt_pk_bf16_f32 v91, v94, v95
	v_permlane16_swap_b32_e32 v120, v122
	v_permlane16_swap_b32_e32 v121, v123
	v_permlane16_swap_b32_e32 v88, v90
	v_permlane16_swap_b32_e32 v89, v91
	global_store_dwordx4 v66, v[120:123], s[84:85] offset:0
	global_store_dwordx4 v66, v[88:91], s[84:85] offset:256
	v_add_u32_e32 v67, 0x90000, v65
	v_cvt_pk_bf16_f32 v32, v32, v33
	v_cvt_pk_bf16_f32 v33, v34, v35
	v_cvt_pk_bf16_f32 v34, v36, v37
	v_cvt_pk_bf16_f32 v35, v38, v39
	v_cvt_pk_bf16_f32 v0, v0, v1
	v_cvt_pk_bf16_f32 v1, v2, v3
	v_cvt_pk_bf16_f32 v2, v4, v5
	v_cvt_pk_bf16_f32 v3, v6, v7
	v_permlane16_swap_b32_e32 v32, v34
	v_permlane16_swap_b32_e32 v33, v35
	v_permlane16_swap_b32_e32 v0, v2
	v_permlane16_swap_b32_e32 v1, v3
	global_store_dwordx4 v67, v[32:35], s[84:85] offset:0
	global_store_dwordx4 v67, v[0:3], s[84:85] offset:256
	v_add_u32_e32 v66, 0xa2000, v65
	v_cvt_pk_bf16_f32 v40, v40, v41
	v_cvt_pk_bf16_f32 v41, v42, v43
	v_cvt_pk_bf16_f32 v42, v44, v45
	v_cvt_pk_bf16_f32 v43, v46, v47
	v_cvt_pk_bf16_f32 v8, v8, v9
	v_cvt_pk_bf16_f32 v9, v10, v11
	v_cvt_pk_bf16_f32 v10, v12, v13
	v_cvt_pk_bf16_f32 v11, v14, v15
	v_permlane16_swap_b32_e32 v40, v42
	v_permlane16_swap_b32_e32 v41, v43
	v_permlane16_swap_b32_e32 v8, v10
	v_permlane16_swap_b32_e32 v9, v11
	global_store_dwordx4 v66, v[40:43], s[84:85] offset:0
	global_store_dwordx4 v66, v[8:11], s[84:85] offset:256
	v_add_u32_e32 v67, 0xb4000, v65
	v_cvt_pk_bf16_f32 v48, v48, v49
	v_cvt_pk_bf16_f32 v49, v50, v51
	v_cvt_pk_bf16_f32 v50, v52, v53
	v_cvt_pk_bf16_f32 v51, v54, v55
	v_cvt_pk_bf16_f32 v16, v16, v17
	v_cvt_pk_bf16_f32 v17, v18, v19
	v_cvt_pk_bf16_f32 v18, v20, v21
	v_cvt_pk_bf16_f32 v19, v22, v23
	v_permlane16_swap_b32_e32 v48, v50
	v_permlane16_swap_b32_e32 v49, v51
	v_permlane16_swap_b32_e32 v16, v18
	v_permlane16_swap_b32_e32 v17, v19
	global_store_dwordx4 v67, v[48:51], s[84:85] offset:0
	global_store_dwordx4 v67, v[16:19], s[84:85] offset:256
	v_add_u32_e32 v66, 0xc6000, v65
	v_cvt_pk_bf16_f32 v56, v56, v57
	v_cvt_pk_bf16_f32 v57, v58, v59
	v_cvt_pk_bf16_f32 v58, v60, v61
	v_cvt_pk_bf16_f32 v59, v62, v63
	v_cvt_pk_bf16_f32 v24, v24, v25
	v_cvt_pk_bf16_f32 v25, v26, v27
	v_cvt_pk_bf16_f32 v26, v28, v29
	v_cvt_pk_bf16_f32 v27, v30, v31
	v_permlane16_swap_b32_e32 v56, v58
	v_permlane16_swap_b32_e32 v57, v59
	v_permlane16_swap_b32_e32 v24, v26
	v_permlane16_swap_b32_e32 v25, v27
	global_store_dwordx4 v66, v[56:59], s[84:85] offset:0
	global_store_dwordx4 v66, v[24:27], s[84:85] offset:256
	s_add_i32 s18, s18, 1
	s_mul_i32 s0, s18, s14
	s_add_i32 s0, s0, s15
	s_cmpk_lt_i32 s0, 0x492
	s_barrier
	s_cbranch_scc0 .LBB0_561

; DI void stb8(bf16_t* p, const F8& f) { *(uint4*)p = pack8(f); }
; template <int MODE>
; DI void gemm_epilogue(const float* Cs, int m0, int n0, const Epi& ep) {
;     ...
; #pragma unroll
;         for (int it = 0; it < 4; ++it) {
;             const int row = (tid >> 4) + 32 * it, cc = (tid & 15) * 8;
;             stb8(ep.b0 + (size_t)(m0 + row) * ep.ld + n0 + cc, ldf8(Cs + row * LDC + cc));
;         }
; template <int MODE>
; DI void gemm_phase(const bf16_t* __restrict__ A, const bf16_t* __restrict__ Bt, int M, int N, int K, const Epi& ep) {
;     ...
; #pragma unroll
;         for (int ai = 0; ai < 2; ++ai)
; #pragma unroll
;             for (int bj = 0; bj < 2; ++bj) {
; #pragma unroll
;                 for (int m = 0; m < 4; ++m)
; #pragma unroll
;                     for (int n = 0; n < 2; ++n)
;                         *(f32x4*)(Cs + (wr * 64 + m * 16 + fr) * LDC + wc * 32 + n * 16 + fq * 4) = acc[ai][bj][m][n];
;                 __syncthreads();
;                 gemm_epilogue<MODE>(Cs, brow + ai * 128, bcol + bj * 128, ep);
;                 __syncthreads();
.LBB0_1015:
	s_or_b64 exec, exec, s[6:7]
	v_mov_b32_e32 v64, v250
	s_waitcnt vmcnt(0)
	s_barrier
	v_and_b32_e32 v64, 15, v250
	v_lshrrev_b32_e32 v66, 8, v250
	v_bfe_u32 v67, v250, 5, 1
	v_lshl_add_u32 v64, v66, 6, v64
	v_bfe_u32 v66, v250, 4, 1
	v_bfe_u32 v212, v250, 6, 2
	v_add_u32_e32 v64, s30, v64
	v_lshlrev_b32_e32 v66, 4, v66
	v_lshl_or_b32 v66, v67, 3, v66
	v_lshlrev_b32_e32 v64, 10, v64
	v_lshl_or_b32 v66, v212, 5, v66
	v_add3_u32 v64, v64, v66, s0
	v_lshlrev_b32_e32 v65, 1, v64
	v_cvt_pk_bf16_f32 v96, v96, v97
	v_cvt_pk_bf16_f32 v97, v98, v99
	v_cvt_pk_bf16_f32 v98, v100, v101
	v_cvt_pk_bf16_f32 v99, v102, v103
	v_cvt_pk_bf16_f32 v222, v222, v223
	v_cvt_pk_bf16_f32 v223, v224, v225
	v_cvt_pk_bf16_f32 v224, v68, v69
	v_cvt_pk_bf16_f32 v225, v70, v71
	v_permlane16_swap_b32_e32 v96, v98
	v_permlane16_swap_b32_e32 v97, v99
	v_permlane16_swap_b32_e32 v222, v224
	v_permlane16_swap_b32_e32 v223, v225
	global_store_dwordx4 v65, v[96:99], s[76:77] offset:0
	global_store_dwordx4 v65, v[222:225], s[76:77] offset:256
	v_add_u32_e32 v66, 0x8000, v65
	v_cvt_pk_bf16_f32 v104, v104, v105
	v_cvt_pk_bf16_f32 v105, v106, v107
	v_cvt_pk_bf16_f32 v106, v108, v109
	v_cvt_pk_bf16_f32 v107, v110, v111
	v_cvt_pk_bf16_f32 v72, v72, v73
	v_cvt_pk_bf16_f32 v73, v74, v75
	v_cvt_pk_bf16_f32 v74, v76, v77
	v_cvt_pk_bf16_f32 v75, v78, v79
	v_permlane16_swap_b32_e32 v104, v106
	v_permlane16_swap_b32_e32 v105, v107
	v_permlane16_swap_b32_e32 v72, v74
	v_permlane16_swap_b32_e32 v73, v75
	global_store_dwordx4 v66, v[104:107], s[76:77] offset:0
	global_store_dwordx4 v66, v[72:75], s[76:77] offset:256
	v_add_u32_e32 v67, 0x10000, v65
	v_cvt_pk_bf16_f32 v112, v112, v113
	v_cvt_pk_bf16_f32 v113, v114, v115
	v_cvt_pk_bf16_f32 v114, v116, v117
	v_cvt_pk_bf16_f32 v115, v118, v119
	v_cvt_pk_bf16_f32 v80, v80, v81
	v_cvt_pk_bf16_f32 v81, v82, v83
	v_cvt_pk_bf16_f32 v82, v84, v85
	v_cvt_pk_bf16_f32 v83, v86, v87
	v_permlane16_swap_b32_e32 v112, v114
	v_permlane16_swap_b32_e32 v113, v115
	v_permlane16_swap_b32_e32 v80, v82
	v_permlane16_swap_b32_e32 v81, v83
	global_store_dwordx4 v67, v[112:115], s[76:77] offset:0
	global_store_dwordx4 v67, v[80:83], s[76:77] offset:256
	v_add_u32_e32 v66, 0x18000, v65
	v_cvt_pk_bf16_f32 v120, v120, v121
	v_cvt_pk_bf16_f32 v121, v122, v123
	v_cvt_pk_bf16_f32 v122, v124, v125
	v_cvt_pk_bf16_f32 v123, v126, v127
	v_cvt_pk_bf16_f32 v88, v88, v89
	v_cvt_pk_bf16_f32 v89, v90, v91
	v_cvt_pk_bf16_f32 v90, v92, v93
	v_cvt_pk_bf16_f32 v91, v94, v95
	v_permlane16_swap_b32_e32 v120, v122
	v_permlane16_swap_b32_e32 v121, v123
	v_permlane16_swap_b32_e32 v88, v90
	v_permlane16_swap_b32_e32 v89, v91
	global_store_dwordx4 v66, v[120:123], s[76:77] offset:0
	global_store_dwordx4 v66, v[88:91], s[76:77] offset:256
	v_add_u32_e32 v67, 0x40000, v65
	v_cvt_pk_bf16_f32 v32, v32, v33
	v_cvt_pk_bf16_f32 v33, v34, v35
	v_cvt_pk_bf16_f32 v34, v36, v37
	v_cvt_pk_bf16_f32 v35, v38, v39
	v_cvt_pk_bf16_f32 v0, v0, v1
	v_cvt_pk_bf16_f32 v1, v2, v3
	v_cvt_pk_bf16_f32 v2, v4, v5
	v_cvt_pk_bf16_f32 v3, v6, v7
	v_permlane16_swap_b32_e32 v32, v34
	v_permlane16_swap_b32_e32 v33, v35
	v_permlane16_swap_b32_e32 v0, v2
	v_permlane16_swap_b32_e32 v1, v3
	global_store_dwordx4 v67, v[32:35], s[76:77] offset:0
	global_store_dwordx4 v67, v[0:3], s[76:77] offset:256
	v_add_u32_e32 v66, 0x48000, v65
	v_cvt_pk_bf16_f32 v40, v40, v41
	v_cvt_pk_bf16_f32 v41, v42, v43
	v_cvt_pk_bf16_f32 v42, v44, v45
	v_cvt_pk_bf16_f32 v43, v46, v47
	v_cvt_pk_bf16_f32 v8, v8, v9
	v_cvt_pk_bf16_f32 v9, v10, v11
	v_cvt_pk_bf16_f32 v10, v12, v13
	v_cvt_pk_bf16_f32 v11, v14, v15
	v_permlane16_swap_b32_e32 v40, v42
	v_permlane16_swap_b32_e32 v41, v43
	v_permlane16_swap_b32_e32 v8, v10
	v_permlane16_swap_b32_e32 v9, v11
	global_store_dwordx4 v66, v[40:43], s[76:77] offset:0
	global_store_dwordx4 v66, v[8:11], s[76:77] offset:256
	v_add_u32_e32 v67, 0x50000, v65
	v_cvt_pk_bf16_f32 v48, v48, v49
	v_cvt_pk_bf16_f32 v49, v50, v51
	v_cvt_pk_bf16_f32 v50, v52, v53
	v_cvt_pk_bf16_f32 v51, v54, v55
	v_cvt_pk_bf16_f32 v16, v16, v17
	v_cvt_pk_bf16_f32 v17, v18, v19
	v_cvt_pk_bf16_f32 v18, v20, v21
	v_cvt_pk_bf16_f32 v19, v22, v23
	v_permlane16_swap_b32_e32 v48, v50
	v_permlane16_swap_b32_e32 v49, v51
	v_permlane16_swap_b32_e32 v16, v18
	v_permlane16_swap_b32_e32 v17, v19
	global_store_dwordx4 v67, v[48:51], s[76:77] offset:0
	global_store_dwordx4 v67, v[16:19], s[76:77] offset:256
	v_add_u32_e32 v66, 0x58000, v65
	v_cvt_pk_bf16_f32 v56, v56, v57
	v_cvt_pk_bf16_f32 v57, v58, v59
	v_cvt_pk_bf16_f32 v58, v60, v61
	v_cvt_pk_bf16_f32 v59, v62, v63
	v_cvt_pk_bf16_f32 v24, v24, v25
	v_cvt_pk_bf16_f32 v25, v26, v27
	v_cvt_pk_bf16_f32 v26, v28, v29
	v_cvt_pk_bf16_f32 v27, v30, v31
	v_permlane16_swap_b32_e32 v56, v58
	v_permlane16_swap_b32_e32 v57, v59
	v_permlane16_swap_b32_e32 v24, v26
	v_permlane16_swap_b32_e32 v25, v27
	global_store_dwordx4 v66, v[56:59], s[76:77] offset:0
	global_store_dwordx4 v66, v[24:27], s[76:77] offset:256
	s_add_i32 s22, s22, 1
	s_mul_i32 s0, s22, s18
	s_add_i32 s0, s0, s19
	s_cmpk_lt_i32 s0, 0x200
	s_barrier
	s_cbranch_scc0 .LBB0_1026

; DI void stb8(bf16_t* p, const F8& f) { *(uint4*)p = pack8(f); }
; template <int MODE>
; DI void gemm_epilogue(const float* Cs, int m0, int n0, const Epi& ep) {
;     ...
; #pragma unroll
;         for (int it = 0; it < 4; ++it) {
;             const int row = (tid >> 4) + 32 * it, cc = (tid & 15) * 8;
;             stb8(ep.b0 + (size_t)(m0 + row) * ep.ld + n0 + cc, ldf8(Cs + row * LDC + cc));
;         }
; template <int MODE>
; DI void gemm_phase(const bf16_t* __restrict__ A, const bf16_t* __restrict__ Bt, int M, int N, int K, const Epi& ep) {
;     ...
; #pragma unroll
;         for (int ai = 0; ai < 2; ++ai)
; #pragma unroll
;             for (int bj = 0; bj < 2; ++bj) {
; #pragma unroll
;                 for (int m = 0; m < 4; ++m)
; #pragma unroll
;                     for (int n = 0; n < 2; ++n)
;                         *(f32x4*)(Cs + (wr * 64 + m * 16 + fr) * LDC + wc * 32 + n * 16 + fq * 4) = acc[ai][bj][m][n];
;                 __syncthreads();
;                 gemm_epilogue<MODE>(Cs, brow + ai * 128, bcol + bj * 128, ep);
;                 __syncthreads();
.LBB0_1444:
	s_or_b64 exec, exec, s[6:7]
	v_mov_b32_e32 v64, v250
	s_waitcnt vmcnt(0)
	s_barrier
	v_and_b32_e32 v64, 15, v250
	v_lshrrev_b32_e32 v66, 8, v250
	v_bfe_u32 v67, v250, 5, 1
	v_lshl_add_u32 v64, v66, 6, v64
	v_bfe_u32 v66, v250, 4, 1
	v_bfe_u32 v212, v250, 6, 2
	v_add_u32_e32 v64, s22, v64
	v_lshlrev_b32_e32 v66, 4, v66
	v_lshl_or_b32 v66, v67, 3, v66
	v_lshlrev_b32_e32 v64, 10, v64
	v_lshl_or_b32 v66, v212, 5, v66
	v_add3_u32 v64, v64, v66, s0
	v_lshlrev_b32_e32 v65, 1, v64
	v_cvt_pk_bf16_f32 v96, v96, v97
	v_cvt_pk_bf16_f32 v97, v98, v99
	v_cvt_pk_bf16_f32 v98, v100, v101
	v_cvt_pk_bf16_f32 v99, v102, v103
	v_cvt_pk_bf16_f32 v222, v222, v223
	v_cvt_pk_bf16_f32 v223, v224, v225
	v_cvt_pk_bf16_f32 v224, v68, v69
	v_cvt_pk_bf16_f32 v225, v70, v71
	v_permlane16_swap_b32_e32 v96, v98
	v_permlane16_swap_b32_e32 v97, v99
	v_permlane16_swap_b32_e32 v222, v224
	v_permlane16_swap_b32_e32 v223, v225
	global_store_dwordx4 v65, v[96:99], s[76:77] offset:0
	global_store_dwordx4 v65, v[222:225], s[76:77] offset:256
	v_add_u32_e32 v66, 0x8000, v65
	v_cvt_pk_bf16_f32 v104, v104, v105
	v_cvt_pk_bf16_f32 v105, v106, v107
	v_cvt_pk_bf16_f32 v106, v108, v109
	v_cvt_pk_bf16_f32 v107, v110, v111
	v_cvt_pk_bf16_f32 v72, v72, v73
	v_cvt_pk_bf16_f32 v73, v74, v75
	v_cvt_pk_bf16_f32 v74, v76, v77
	v_cvt_pk_bf16_f32 v75, v78, v79
	v_permlane16_swap_b32_e32 v104, v106
	v_permlane16_swap_b32_e32 v105, v107
	v_permlane16_swap_b32_e32 v72, v74
	v_permlane16_swap_b32_e32 v73, v75
	global_store_dwordx4 v66, v[104:107], s[76:77] offset:0
	global_store_dwordx4 v66, v[72:75], s[76:77] offset:256
	v_add_u32_e32 v67, 0x10000, v65
	v_cvt_pk_bf16_f32 v112, v112, v113
	v_cvt_pk_bf16_f32 v113, v114, v115
	v_cvt_pk_bf16_f32 v114, v116, v117
	v_cvt_pk_bf16_f32 v115, v118, v119
	v_cvt_pk_bf16_f32 v80, v80, v81
	v_cvt_pk_bf16_f32 v81, v82, v83
	v_cvt_pk_bf16_f32 v82, v84, v85
	v_cvt_pk_bf16_f32 v83, v86, v87
	v_permlane16_swap_b32_e32 v112, v114
	v_permlane16_swap_b32_e32 v113, v115
	v_permlane16_swap_b32_e32 v80, v82
	v_permlane16_swap_b32_e32 v81, v83
	global_store_dwordx4 v67, v[112:115], s[76:77] offset:0
	global_store_dwordx4 v67, v[80:83], s[76:77] offset:256
	v_add_u32_e32 v66, 0x18000, v65
	v_cvt_pk_bf16_f32 v120, v120, v121
	v_cvt_pk_bf16_f32 v121, v122, v123
	v_cvt_pk_bf16_f32 v122, v124, v125
	v_cvt_pk_bf16_f32 v123, v126, v127
	v_cvt_pk_bf16_f32 v88, v88, v89
	v_cvt_pk_bf16_f32 v89, v90, v91
	v_cvt_pk_bf16_f32 v90, v92, v93
	v_cvt_pk_bf16_f32 v91, v94, v95
	v_permlane16_swap_b32_e32 v120, v122
	v_permlane16_swap_b32_e32 v121, v123
	v_permlane16_swap_b32_e32 v88, v90
	v_permlane16_swap_b32_e32 v89, v91
	global_store_dwordx4 v66, v[120:123], s[76:77] offset:0
	global_store_dwordx4 v66, v[88:91], s[76:77] offset:256
	v_add_u32_e32 v67, 0x40000, v65
	v_cvt_pk_bf16_f32 v32, v32, v33
	v_cvt_pk_bf16_f32 v33, v34, v35
	v_cvt_pk_bf16_f32 v34, v36, v37
	v_cvt_pk_bf16_f32 v35, v38, v39
	v_cvt_pk_bf16_f32 v0, v0, v1
	v_cvt_pk_bf16_f32 v1, v2, v3
	v_cvt_pk_bf16_f32 v2, v4, v5
	v_cvt_pk_bf16_f32 v3, v6, v7
	v_permlane16_swap_b32_e32 v32, v34
	v_permlane16_swap_b32_e32 v33, v35
	v_permlane16_swap_b32_e32 v0, v2
	v_permlane16_swap_b32_e32 v1, v3
	global_store_dwordx4 v67, v[32:35], s[76:77] offset:0
	global_store_dwordx4 v67, v[0:3], s[76:77] offset:256
	v_add_u32_e32 v66, 0x48000, v65
	v_cvt_pk_bf16_f32 v40, v40, v41
	v_cvt_pk_bf16_f32 v41, v42, v43
	v_cvt_pk_bf16_f32 v42, v44, v45
	v_cvt_pk_bf16_f32 v43, v46, v47
	v_cvt_pk_bf16_f32 v8, v8, v9
	v_cvt_pk_bf16_f32 v9, v10, v11
	v_cvt_pk_bf16_f32 v10, v12, v13
	v_cvt_pk_bf16_f32 v11, v14, v15
	v_permlane16_swap_b32_e32 v40, v42
	v_permlane16_swap_b32_e32 v41, v43
	v_permlane16_swap_b32_e32 v8, v10
	v_permlane16_swap_b32_e32 v9, v11
	global_store_dwordx4 v66, v[40:43], s[76:77] offset:0
	global_store_dwordx4 v66, v[8:11], s[76:77] offset:256
	v_add_u32_e32 v67, 0x50000, v65
	v_cvt_pk_bf16_f32 v48, v48, v49
	v_cvt_pk_bf16_f32 v49, v50, v51
	v_cvt_pk_bf16_f32 v50, v52, v53
	v_cvt_pk_bf16_f32 v51, v54, v55
	v_cvt_pk_bf16_f32 v16, v16, v17
	v_cvt_pk_bf16_f32 v17, v18, v19
	v_cvt_pk_bf16_f32 v18, v20, v21
	v_cvt_pk_bf16_f32 v19, v22, v23
	v_permlane16_swap_b32_e32 v48, v50
	v_permlane16_swap_b32_e32 v49, v51
	v_permlane16_swap_b32_e32 v16, v18
	v_permlane16_swap_b32_e32 v17, v19
	global_store_dwordx4 v67, v[48:51], s[76:77] offset:0
	global_store_dwordx4 v67, v[16:19], s[76:77] offset:256
	v_add_u32_e32 v66, 0x58000, v65
	v_cvt_pk_bf16_f32 v56, v56, v57
	v_cvt_pk_bf16_f32 v57, v58, v59
	v_cvt_pk_bf16_f32 v58, v60, v61
	v_cvt_pk_bf16_f32 v59, v62, v63
	v_cvt_pk_bf16_f32 v24, v24, v25
	v_cvt_pk_bf16_f32 v25, v26, v27
	v_cvt_pk_bf16_f32 v26, v28, v29
	v_cvt_pk_bf16_f32 v27, v30, v31
	v_permlane16_swap_b32_e32 v56, v58
	v_permlane16_swap_b32_e32 v57, v59
	v_permlane16_swap_b32_e32 v24, v26
	v_permlane16_swap_b32_e32 v25, v27
	global_store_dwordx4 v66, v[56:59], s[76:77] offset:0
	global_store_dwordx4 v66, v[24:27], s[76:77] offset:256
	s_add_i32 s18, s18, 1
	s_mul_i32 s0, s18, s14
	s_add_i32 s0, s0, s15
	s_cmpk_lt_i32 s0, 0x200
	s_barrier
	s_cbranch_scc0 .LBB0_1455
